# attention rescale: 16 packed v_pk_mul_f32 per block split into scalar v_mul_f32 pairs (bit-identical)
# baseline (speedup 1.0000x reference)
; #define LAS __attribute__((address_space(3)))
; #define MFMA32(a, b, c) __builtin_amdgcn_mfma_f32_32x32x16_bf16((a), (b), (c), 0, 0, 0)
; template <int MODE, bool UNI>
; DI void attn_compute(const bf16x8 (&qf)[4], const bf16x8 (&kf)[4], const bf16x8 (&vf)[2][2], int kt, int d00, const float* lut, float ubias, AttnSt& st,
;                      unsigned W, int win, int dmask, bool lane_sel) {
;     ...
;     const int d0 = d00 - s0;
;     const LAS float* lb = (const LAS float*)lut + ((MODE == 4) ? 16 * (d0 - 23) : (d0 - 23));
;     float bia[16];
;     if (!UNI) {
; #pragma unroll
;         for (int i = 0; i < 16; ++i) { const int ci = 16 * (i >> 3) + (i & 7); bia[i] = (MODE == 4) ? lb[16 * (23 - ci)] : lb[23 - ci]; }
;     }
;     f32x16 sx;
; #pragma unroll
;     for (int i = 0; i < 16; ++i) sx[i] = 0.f;
; #pragma unroll
;     for (int ks = 0; ks < 4; ++ks) sx = MFMA32(kf[ks], qf[ks], sx);
;     asm volatile("s_waitcnt lgkmcnt(0)" ::: "memory");
;     float sv[16]; float mx = NEGF;
; #pragma unroll
;     for (int i = 0; i < 16; ++i) {
;         const int ci = 16 * (i >> 3) + (i & 7);
;         const int dist = d0 - ci;
;         bool v;
;         if (MODE == 0) v = ((W >> ci) & 1u) != 0u;
;         else if (MODE == 1) v = ((unsigned)dist <= (unsigned)win) && ((dist & dmask) == 0);
;         else if (MODE == 2) v = lane_sel;
;         else v = dist >= 0;
;         const float bias = UNI ? ubias : bia[i];
;         float s = fmaf(sx[i], SC2, bias);
;         if (MODE == 0) { const unsigned t = (unsigned)__builtin_amdgcn_sbfe((int)W, ci, 1);
;             s = __uint_as_float((__float_as_uint(s) & t) | (__float_as_uint(NEGF) & ~t)); }
;         else s = v ? s : NEGF;
;         sv[i] = s; mx = fmaxf(mx, s);
;     }
;     mx = fmaxf(mx, __shfl_xor(mx, 32));
;     const float mnew = fmaxf(st.m, mx);
;     const float msafe = (mnew > -1e29f) ? mnew : 0.f;
;     if (__ballot(mnew > st.m) != 0ull) {
;         const float alpha = __builtin_amdgcn_exp2f(st.m - msafe);
;         st.l *= alpha; st.m = mnew;
; #pragma unroll
;         for (int i = 0; i < 16; ++i) { st.o0[i] *= alpha; st.o1[i] *= alpha; }
;     }
.LBB0_289:
	s_and_b64 vcc, exec, s[46:47]
	s_cbranch_vccz .LBB0_294
	s_waitcnt lgkmcnt(0)
	v_mfma_f32_32x32x16_bf16 v[34:49], v[106:109], v[78:81], 0
	ds_read2_b32 v[50:51], v0 offset0:22 offset1:23
	ds_read2_b32 v[52:53], v0 offset0:20 offset1:21
	ds_read2_b32 v[54:55], v0 offset0:18 offset1:19
	ds_read2_b32 v[56:57], v0 offset0:16 offset1:17
	v_add_u32_e32 v106, 0x98, v151
	v_cmp_gt_u32_e32 vcc, s95, v106
	v_add_u32_e32 v107, 18, v151
	ds_read2_b32 v[58:59], v0 offset0:6 offset1:7
	ds_read2_b32 v[60:61], v0 offset0:4 offset1:5
	ds_read2_b32 v[62:63], v0 offset0:2 offset1:3
	ds_read2_b32 v[64:65], v0 offset1:1
	v_mfma_f32_32x32x16_bf16 v[34:49], v[110:113], v[74:77], v[34:49]
	v_mfma_f32_32x32x16_bf16 v[34:49], v[102:105], v[70:73], v[34:49]
	v_add_u32_e32 v102, 22, v151
	v_add_u32_e32 v103, 21, v151
	v_add_u32_e32 v104, 20, v151
	v_add_u32_e32 v105, 19, v151
	v_mfma_f32_32x32x16_bf16 v[34:49], v[98:101], v[66:69], v[34:49]
	s_waitcnt lgkmcnt(0)
	s_nop 10
	v_fmamk_f32 v34, v34, 0x3e38aa3b, v51
	v_fmac_f32_e32 v50, 0x3e38aa3b, v35
	v_cndmask_b32_e32 v35, v239, v34, vcc
	v_cmp_lt_u32_e32 vcc, s13, v102
	v_fmamk_f32 v51, v36, 0x3e38aa3b, v53
	v_fmac_f32_e32 v52, 0x3e38aa3b, v37
	v_cndmask_b32_e32 v36, v239, v50, vcc
	v_cmp_lt_u32_e32 vcc, s13, v103
	v_fmamk_f32 v38, v38, 0x3e38aa3b, v55
	v_fmac_f32_e32 v54, 0x3e38aa3b, v39
	v_cndmask_b32_e32 v37, v239, v51, vcc
	v_cmp_lt_u32_e32 vcc, s13, v104
	v_add_u32_e32 v51, 17, v151
	v_fmamk_f32 v40, v40, 0x3e38aa3b, v57
	v_cndmask_b32_e32 v34, v239, v52, vcc
	v_cmp_lt_u32_e32 vcc, s13, v105
	v_fmac_f32_e32 v56, 0x3e38aa3b, v41
	v_fmamk_f32 v42, v42, 0x3e38aa3b, v59
	v_cndmask_b32_e32 v39, v239, v38, vcc
	v_cmp_lt_u32_e32 vcc, s13, v107
	v_max3_f32 v38, v35, s30, v36
	v_fmac_f32_e32 v58, 0x3e38aa3b, v43
	v_cndmask_b32_e32 v50, v239, v54, vcc
	v_cmp_lt_u32_e32 vcc, s13, v51
	v_max3_f32 v38, v38, v37, v34
	v_fmamk_f32 v44, v44, 0x3e38aa3b, v61
	v_cndmask_b32_e32 v51, v239, v40, vcc
	v_add_u32_e32 v40, 16, v151
	v_cmp_lt_u32_e32 vcc, s13, v40
	v_add_u32_e32 v40, 7, v151
	v_max3_f32 v38, v38, v39, v50
	v_cndmask_b32_e32 v41, v239, v56, vcc
	v_cmp_lt_u32_e32 vcc, s13, v40
	v_add_u32_e32 v40, 6, v151
	v_fmac_f32_e32 v60, 0x3e38aa3b, v45
	v_cndmask_b32_e32 v42, v239, v42, vcc
	v_cmp_lt_u32_e32 vcc, s13, v40
	v_add_u32_e32 v40, 5, v151
	v_max3_f32 v38, v38, v51, v41
	v_cndmask_b32_e32 v43, v239, v58, vcc
	v_cmp_lt_u32_e32 vcc, s13, v40
	v_add_u32_e32 v40, 4, v151
	v_fmamk_f32 v46, v46, 0x3e38aa3b, v63
	v_cndmask_b32_e32 v44, v239, v44, vcc
	v_cmp_lt_u32_e32 vcc, s13, v40
	v_add_u32_e32 v40, 3, v151
	v_max3_f32 v38, v38, v42, v43
	v_cndmask_b32_e32 v45, v239, v60, vcc
	v_cmp_lt_u32_e32 vcc, s13, v40
	v_add_u32_e32 v40, 2, v151
	v_fmac_f32_e32 v62, 0x3e38aa3b, v47
	v_cndmask_b32_e32 v46, v239, v46, vcc
	v_cmp_lt_u32_e32 vcc, s13, v40
	v_max3_f32 v38, v38, v44, v45
	v_fmamk_f32 v48, v48, 0x3e38aa3b, v65
	v_cndmask_b32_e32 v47, v239, v62, vcc
	v_max3_f32 v40, v38, v46, v47
	v_add_u32_e32 v38, 1, v151
	v_cmp_lt_u32_e32 vcc, s13, v38
	v_fmac_f32_e32 v64, 0x3e38aa3b, v49
	s_nop 0
	v_cndmask_b32_e32 v48, v239, v48, vcc
	v_cmp_lt_u32_e32 vcc, s13, v151
	s_nop 1
	v_cndmask_b32_e32 v38, v239, v64, vcc
	v_max3_f32 v40, v40, v48, v38
	v_mov_b32_e32 v49, v40
	s_nop 1
	v_permlane32_swap_b32_e32 v49, v40
	s_waitcnt lgkmcnt(0)
	v_max3_f32 v169, v153, v40, v49
	v_cmp_lt_f32_e32 vcc, s12, v169
	s_nop 1
	v_cndmask_b32_e32 v40, 0, v169, vcc
	v_cmp_gt_f32_e32 vcc, v169, v153
	s_cbranch_vccz .LBB0_292
	v_sub_f32_e32 v49, v153, v40
	v_exp_f32_e32 v52, v49
	s_nop 0
	v_mul_f32_e32 v150, v150, v52
	v_mul_f32_e32 v16, v52, v16
	v_mul_f32_e32 v17, v52, v17
	v_mul_f32_e32 v14, v52, v14
	v_mul_f32_e32 v15, v52, v15
	v_mul_f32_e32 v12, v52, v12
	v_mul_f32_e32 v13, v52, v13
	v_mul_f32_e32 v10, v52, v10
	v_mul_f32_e32 v11, v52, v11
	v_mul_f32_e32 v8, v52, v8
	v_mul_f32_e32 v9, v52, v9
	v_mul_f32_e32 v6, v52, v6
	v_mul_f32_e32 v7, v52, v7
	v_mul_f32_e32 v4, v52, v4
	v_mul_f32_e32 v5, v52, v5
	v_mul_f32_e32 v2, v52, v2
	v_mul_f32_e32 v3, v52, v3
	v_mul_f32_e32 v32, v52, v32
	v_mul_f32_e32 v33, v52, v33
	v_mul_f32_e32 v30, v52, v30
	v_mul_f32_e32 v31, v52, v31
	v_mul_f32_e32 v28, v52, v28
	v_mul_f32_e32 v29, v52, v29
	v_mul_f32_e32 v26, v52, v26
	v_mul_f32_e32 v27, v52, v27
	v_mul_f32_e32 v24, v52, v24
	v_mul_f32_e32 v25, v52, v25
	v_mul_f32_e32 v22, v52, v22
	v_mul_f32_e32 v23, v52, v23
	v_mul_f32_e32 v20, v52, v20
	v_mul_f32_e32 v21, v52, v21
	v_mul_f32_e32 v18, v52, v18
	v_mul_f32_e32 v19, v52, v19
	s_branch .LBB0_293

; #define LAS __attribute__((address_space(3)))
; #define MFMA32(a, b, c) __builtin_amdgcn_mfma_f32_32x32x16_bf16((a), (b), (c), 0, 0, 0)
; template <int MODE, bool UNI>
; DI void attn_compute(const bf16x8 (&qf)[4], const bf16x8 (&kf)[4], const bf16x8 (&vf)[2][2], int kt, int d00, const float* lut, float ubias, AttnSt& st,
;                      unsigned W, int win, int dmask, bool lane_sel) {
;     ...
;     const int d0 = d00 - s0;
;     const LAS float* lb = (const LAS float*)lut + ((MODE == 4) ? 16 * (d0 - 23) : (d0 - 23));
;     float bia[16];
;     if (!UNI) {
; #pragma unroll
;         for (int i = 0; i < 16; ++i) { const int ci = 16 * (i >> 3) + (i & 7); bia[i] = (MODE == 4) ? lb[16 * (23 - ci)] : lb[23 - ci]; }
;     }
;     f32x16 sx;
; #pragma unroll
;     for (int i = 0; i < 16; ++i) sx[i] = 0.f;
; #pragma unroll
;     for (int ks = 0; ks < 4; ++ks) sx = MFMA32(kf[ks], qf[ks], sx);
;     asm volatile("s_waitcnt lgkmcnt(0)" ::: "memory");
;     float sv[16]; float mx = NEGF;
; #pragma unroll
;     for (int i = 0; i < 16; ++i) {
;         const int ci = 16 * (i >> 3) + (i & 7);
;         const int dist = d0 - ci;
;         bool v;
;         if (MODE == 0) v = ((W >> ci) & 1u) != 0u;
;         else if (MODE == 1) v = ((unsigned)dist <= (unsigned)win) && ((dist & dmask) == 0);
;         else if (MODE == 2) v = lane_sel;
;         else v = dist >= 0;
;         const float bias = UNI ? ubias : bia[i];
;         float s = fmaf(sx[i], SC2, bias);
;         if (MODE == 0) { const unsigned t = (unsigned)__builtin_amdgcn_sbfe((int)W, ci, 1);
;             s = __uint_as_float((__float_as_uint(s) & t) | (__float_as_uint(NEGF) & ~t)); }
;         else s = v ? s : NEGF;
;         sv[i] = s; mx = fmaxf(mx, s);
;     }
;     mx = fmaxf(mx, __shfl_xor(mx, 32));
;     const float mnew = fmaxf(st.m, mx);
;     const float msafe = (mnew > -1e29f) ? mnew : 0.f;
;     if (__ballot(mnew > st.m) != 0ull) {
;         const float alpha = __builtin_amdgcn_exp2f(st.m - msafe);
;         st.l *= alpha; st.m = mnew;
; #pragma unroll
;         for (int i = 0; i < 16; ++i) { st.o0[i] *= alpha; st.o1[i] *= alpha; }
;     }
.LBB0_308:
	s_and_b64 vcc, exec, s[46:47]
	s_cbranch_vccz .LBB0_313
	s_waitcnt lgkmcnt(0)
	v_mfma_f32_32x32x16_bf16 v[2:17], v[106:109], v[78:81], 0
	ds_read2_b32 v[50:51], v169 offset0:22 offset1:23
	ds_read2_b32 v[52:53], v169 offset0:20 offset1:21
	ds_read2_b32 v[54:55], v169 offset0:18 offset1:19
	ds_read2_b32 v[56:57], v169 offset0:16 offset1:17
	v_add_u32_e32 v106, 0x98, v170
	v_cmp_gt_u32_e32 vcc, s95, v106
	v_add_u32_e32 v107, 18, v170
	ds_read2_b32 v[58:59], v169 offset0:6 offset1:7
	ds_read2_b32 v[60:61], v169 offset0:4 offset1:5
	ds_read2_b32 v[62:63], v169 offset0:2 offset1:3
	ds_read2_b32 v[64:65], v169 offset1:1
	v_mfma_f32_32x32x16_bf16 v[2:17], v[110:113], v[74:77], v[2:17]
	v_mfma_f32_32x32x16_bf16 v[2:17], v[102:105], v[70:73], v[2:17]
	v_add_u32_e32 v102, 22, v170
	v_add_u32_e32 v103, 21, v170
	v_add_u32_e32 v104, 20, v170
	v_add_u32_e32 v105, 19, v170
	v_mfma_f32_32x32x16_bf16 v[2:17], v[98:101], v[66:69], v[2:17]
	s_waitcnt lgkmcnt(0)
	s_nop 10
	v_fmamk_f32 v2, v2, 0x3e38aa3b, v51
	v_fmac_f32_e32 v50, 0x3e38aa3b, v3
	v_cndmask_b32_e32 v3, v239, v2, vcc
	v_cmp_lt_u32_e32 vcc, s13, v102
	v_fmamk_f32 v51, v4, 0x3e38aa3b, v53
	v_fmac_f32_e32 v52, 0x3e38aa3b, v5
	v_cndmask_b32_e32 v4, v239, v50, vcc
	v_cmp_lt_u32_e32 vcc, s13, v103
	v_fmamk_f32 v6, v6, 0x3e38aa3b, v55
	v_fmac_f32_e32 v54, 0x3e38aa3b, v7
	v_cndmask_b32_e32 v5, v239, v51, vcc
	v_cmp_lt_u32_e32 vcc, s13, v104
	v_add_u32_e32 v51, 17, v170
	v_fmamk_f32 v8, v8, 0x3e38aa3b, v57
	v_cndmask_b32_e32 v2, v239, v52, vcc
	v_cmp_lt_u32_e32 vcc, s13, v105
	v_fmac_f32_e32 v56, 0x3e38aa3b, v9
	v_fmamk_f32 v10, v10, 0x3e38aa3b, v59
	v_cndmask_b32_e32 v7, v239, v6, vcc
	v_cmp_lt_u32_e32 vcc, s13, v107
	v_max3_f32 v6, v3, s30, v4
	v_fmac_f32_e32 v58, 0x3e38aa3b, v11
	v_cndmask_b32_e32 v50, v239, v54, vcc
	v_cmp_lt_u32_e32 vcc, s13, v51
	v_max3_f32 v6, v6, v5, v2
	v_fmamk_f32 v12, v12, 0x3e38aa3b, v61
	v_cndmask_b32_e32 v51, v239, v8, vcc
	v_add_u32_e32 v8, 16, v170
	v_cmp_lt_u32_e32 vcc, s13, v8
	v_add_u32_e32 v8, 7, v170
	v_max3_f32 v6, v6, v7, v50
	v_cndmask_b32_e32 v9, v239, v56, vcc
	v_cmp_lt_u32_e32 vcc, s13, v8
	v_add_u32_e32 v8, 6, v170
	v_fmac_f32_e32 v60, 0x3e38aa3b, v13
	v_cndmask_b32_e32 v10, v239, v10, vcc
	v_cmp_lt_u32_e32 vcc, s13, v8
	v_add_u32_e32 v8, 5, v170
	v_max3_f32 v6, v6, v51, v9
	v_cndmask_b32_e32 v11, v239, v58, vcc
	v_cmp_lt_u32_e32 vcc, s13, v8
	v_add_u32_e32 v8, 4, v170
	v_fmamk_f32 v14, v14, 0x3e38aa3b, v63
	v_cndmask_b32_e32 v12, v239, v12, vcc
	v_cmp_lt_u32_e32 vcc, s13, v8
	v_add_u32_e32 v8, 3, v170
	v_max3_f32 v6, v6, v10, v11
	v_cndmask_b32_e32 v13, v239, v60, vcc
	v_cmp_lt_u32_e32 vcc, s13, v8
	v_add_u32_e32 v8, 2, v170
	v_fmac_f32_e32 v62, 0x3e38aa3b, v15
	v_cndmask_b32_e32 v14, v239, v14, vcc
	v_cmp_lt_u32_e32 vcc, s13, v8
	v_max3_f32 v6, v6, v12, v13
	v_fmamk_f32 v16, v16, 0x3e38aa3b, v65
	v_cndmask_b32_e32 v15, v239, v62, vcc
	v_max3_f32 v8, v6, v14, v15
	v_add_u32_e32 v6, 1, v170
	v_cmp_lt_u32_e32 vcc, s13, v6
	v_fmac_f32_e32 v64, 0x3e38aa3b, v17
	s_nop 0
	v_cndmask_b32_e32 v16, v239, v16, vcc
	v_cmp_lt_u32_e32 vcc, s13, v170
	s_nop 1
	v_cndmask_b32_e32 v6, v239, v64, vcc
	v_max3_f32 v8, v8, v16, v6
	v_mov_b32_e32 v17, v8
	s_nop 1
	v_permlane32_swap_b32_e32 v17, v8
	s_waitcnt lgkmcnt(0)
	v_max3_f32 v173, v172, v8, v17
	v_cmp_lt_f32_e32 vcc, s12, v173
	s_nop 1
	v_cndmask_b32_e32 v8, 0, v173, vcc
	v_cmp_gt_f32_e32 vcc, v173, v172
	s_cbranch_vccz .LBB0_311
	v_sub_f32_e32 v17, v172, v8
	v_exp_f32_e32 v52, v17
	s_nop 0
	v_mul_f32_e32 v149, v149, v52
	v_mul_f32_e32 v48, v52, v48
	v_mul_f32_e32 v49, v52, v49
	v_mul_f32_e32 v46, v52, v46
	v_mul_f32_e32 v47, v52, v47
	v_mul_f32_e32 v44, v52, v44
	v_mul_f32_e32 v45, v52, v45
	v_mul_f32_e32 v42, v52, v42
	v_mul_f32_e32 v43, v52, v43
	v_mul_f32_e32 v40, v52, v40
	v_mul_f32_e32 v41, v52, v41
	v_mul_f32_e32 v38, v52, v38
	v_mul_f32_e32 v39, v52, v39
	v_mul_f32_e32 v36, v52, v36
	v_mul_f32_e32 v37, v52, v37
	v_mul_f32_e32 v34, v52, v34
	v_mul_f32_e32 v35, v52, v35
	v_mul_f32_e32 v32, v52, v32
	v_mul_f32_e32 v33, v52, v33
	v_mul_f32_e32 v30, v52, v30
	v_mul_f32_e32 v31, v52, v31
	v_mul_f32_e32 v28, v52, v28
	v_mul_f32_e32 v29, v52, v29
	v_mul_f32_e32 v26, v52, v26
	v_mul_f32_e32 v27, v52, v27
	v_mul_f32_e32 v24, v52, v24
	v_mul_f32_e32 v25, v52, v25
	v_mul_f32_e32 v22, v52, v22
	v_mul_f32_e32 v23, v52, v23
	v_mul_f32_e32 v20, v52, v20
	v_mul_f32_e32 v21, v52, v21
	v_mul_f32_e32 v18, v52, v18
	v_mul_f32_e32 v19, v52, v19
	s_branch .LBB0_312

; #define LAS __attribute__((address_space(3)))
; #define MFMA32(a, b, c) __builtin_amdgcn_mfma_f32_32x32x16_bf16((a), (b), (c), 0, 0, 0)
; template <int MODE, bool UNI>
; DI void attn_compute(const bf16x8 (&qf)[4], const bf16x8 (&kf)[4], const bf16x8 (&vf)[2][2], int kt, int d00, const float* lut, float ubias, AttnSt& st,
;                      unsigned W, int win, int dmask, bool lane_sel) {
;     ...
;     const int d0 = d00 - s0;
;     const LAS float* lb = (const LAS float*)lut + ((MODE == 4) ? 16 * (d0 - 23) : (d0 - 23));
;     float bia[16];
;     if (!UNI) {
; #pragma unroll
;         for (int i = 0; i < 16; ++i) { const int ci = 16 * (i >> 3) + (i & 7); bia[i] = (MODE == 4) ? lb[16 * (23 - ci)] : lb[23 - ci]; }
;     }
;     f32x16 sx;
; #pragma unroll
;     for (int i = 0; i < 16; ++i) sx[i] = 0.f;
; #pragma unroll
;     for (int ks = 0; ks < 4; ++ks) sx = MFMA32(kf[ks], qf[ks], sx);
;     asm volatile("s_waitcnt lgkmcnt(0)" ::: "memory");
;     float sv[16]; float mx = NEGF;
; #pragma unroll
;     for (int i = 0; i < 16; ++i) {
;         const int ci = 16 * (i >> 3) + (i & 7);
;         const int dist = d0 - ci;
;         bool v;
;         if (MODE == 0) v = ((W >> ci) & 1u) != 0u;
;         else if (MODE == 1) v = ((unsigned)dist <= (unsigned)win) && ((dist & dmask) == 0);
;         else if (MODE == 2) v = lane_sel;
;         else v = dist >= 0;
;         const float bias = UNI ? ubias : bia[i];
;         float s = fmaf(sx[i], SC2, bias);
;         if (MODE == 0) { const unsigned t = (unsigned)__builtin_amdgcn_sbfe((int)W, ci, 1);
;             s = __uint_as_float((__float_as_uint(s) & t) | (__float_as_uint(NEGF) & ~t)); }
;         else s = v ? s : NEGF;
;         sv[i] = s; mx = fmaxf(mx, s);
;     }
;     mx = fmaxf(mx, __shfl_xor(mx, 32));
;     const float mnew = fmaxf(st.m, mx);
;     const float msafe = (mnew > -1e29f) ? mnew : 0.f;
;     if (__ballot(mnew > st.m) != 0ull) {
;         const float alpha = __builtin_amdgcn_exp2f(st.m - msafe);
;         st.l *= alpha; st.m = mnew;
; #pragma unroll
;         for (int i = 0; i < 16; ++i) { st.o0[i] *= alpha; st.o1[i] *= alpha; }
;     }
.LBB0_324:
	s_waitcnt lgkmcnt(0)
	v_mfma_f32_32x32x16_bf16 v[34:49], v[34:37], v[62:65], 0
	v_lshrrev_b32_e32 v150, v137, v106
	v_bfe_i32 v151, v150, 4, 1
	v_bfe_i32 v152, v150, 5, 1
	v_bfe_i32 v153, v150, 6, 1
	v_mfma_f32_32x32x16_bf16 v[34:49], v[90:93], v[58:61], v[34:49]
	ds_read2_b32 v[90:91], v103 offset0:22 offset1:23
	ds_read2_b32 v[92:93], v103 offset0:20 offset1:21
	ds_read2_b32 v[106:107], v103 offset0:18 offset1:19
	ds_read2_b32 v[108:109], v103 offset0:16 offset1:17
	ds_read2_b32 v[110:111], v103 offset0:6 offset1:7
	ds_read2_b32 v[112:113], v103 offset0:4 offset1:5
	ds_read2_b32 v[146:147], v103 offset0:2 offset1:3
	ds_read2_b32 v[148:149], v103 offset1:1
	v_mfma_f32_32x32x16_bf16 v[34:49], v[86:89], v[54:57], v[34:49]
	v_bfe_i32 v88, v150, 2, 1
	v_bfe_i32 v86, v150, 0, 1
	v_bfe_i32 v87, v150, 1, 1
	v_bfe_i32 v89, v150, 3, 1
	v_mfma_f32_32x32x16_bf16 v[34:49], v[82:85], v[50:53], v[34:49]
	s_waitcnt lgkmcnt(0)
	s_nop 10
	v_fmac_f32_e32 v90, 0x3e38aa3b, v35
	v_fmamk_f32 v35, v36, 0x3e38aa3b, v93
	v_fmamk_f32 v36, v38, 0x3e38aa3b, v107
	v_bitop3_b32 v83, v35, s30, v88 bitop3:0xe4
	v_fmac_f32_e32 v108, 0x3e38aa3b, v41
	v_bfe_i32 v35, v150, 7, 1
	v_fmamk_f32 v34, v34, 0x3e38aa3b, v91
	v_fmac_f32_e32 v92, 0x3e38aa3b, v37
	v_fmac_f32_e32 v106, 0x3e38aa3b, v39
	v_fmamk_f32 v37, v40, 0x3e38aa3b, v109
	v_bitop3_b32 v39, v36, s30, v151 bitop3:0xe4
	v_bitop3_b32 v40, v108, s30, v35 bitop3:0xe4
	v_fmamk_f32 v35, v42, 0x3e38aa3b, v111
	v_bfe_i32 v36, v150, 16, 1
	v_bitop3_b32 v85, v34, s30, v86 bitop3:0xe4
	v_bitop3_b32 v84, v90, s30, v87 bitop3:0xe4
	v_bitop3_b32 v41, v35, s30, v36 bitop3:0xe4
	v_fmac_f32_e32 v110, 0x3e38aa3b, v43
	v_bfe_i32 v35, v150, 17, 1
	v_bitop3_b32 v82, v92, s30, v89 bitop3:0xe4
	v_max3_f32 v34, v85, s30, v84
	v_bitop3_b32 v42, v110, s30, v35 bitop3:0xe4
	v_fmamk_f32 v35, v44, 0x3e38aa3b, v113
	v_bfe_i32 v36, v150, 18, 1
	v_bitop3_b32 v38, v106, s30, v152 bitop3:0xe4
	v_max3_f32 v34, v34, v83, v82
	v_bitop3_b32 v43, v35, s30, v36 bitop3:0xe4
	v_fmac_f32_e32 v112, 0x3e38aa3b, v45
	v_bfe_i32 v35, v150, 19, 1
	v_bitop3_b32 v37, v37, s30, v153 bitop3:0xe4
	v_max3_f32 v34, v34, v39, v38
	v_bitop3_b32 v44, v112, s30, v35 bitop3:0xe4
	v_fmamk_f32 v35, v46, 0x3e38aa3b, v147
	v_bfe_i32 v36, v150, 20, 1
	v_max3_f32 v34, v34, v37, v40
	v_bitop3_b32 v45, v35, s30, v36 bitop3:0xe4
	v_fmac_f32_e32 v146, 0x3e38aa3b, v47
	v_bfe_i32 v35, v150, 21, 1
	v_max3_f32 v34, v34, v41, v42
	v_bitop3_b32 v46, v146, s30, v35 bitop3:0xe4
	v_fmamk_f32 v35, v48, 0x3e38aa3b, v149
	v_bfe_i32 v36, v150, 22, 1
	v_max3_f32 v34, v34, v43, v44
	v_bitop3_b32 v47, v35, s30, v36 bitop3:0xe4
	v_fmac_f32_e32 v148, 0x3e38aa3b, v49
	v_bfe_i32 v35, v150, 23, 1
	v_max3_f32 v34, v34, v45, v46
	v_bitop3_b32 v35, v148, s30, v35 bitop3:0xe4
	v_max3_f32 v34, v34, v47, v35
	v_mov_b32_e32 v36, v34
	s_nop 1
	v_permlane32_swap_b32_e32 v36, v34
	s_waitcnt lgkmcnt(0)
	v_max3_f32 v34, v105, v34, v36
	v_cmp_lt_f32_e32 vcc, s12, v34
	s_nop 1
	v_cndmask_b32_e32 v36, 0, v34, vcc
	v_cmp_gt_f32_e32 vcc, v34, v105
	s_cbranch_vccz .LBB0_326
	v_sub_f32_e32 v48, v105, v36
	v_exp_f32_e32 v48, v48
	s_nop 0
	v_mul_f32_e32 v102, v102, v48
	v_mul_f32_e32 v32, v48, v32
	v_mul_f32_e32 v33, v48, v33
	v_mul_f32_e32 v30, v48, v30
	v_mul_f32_e32 v31, v48, v31
	v_mul_f32_e32 v28, v48, v28
	v_mul_f32_e32 v29, v48, v29
	v_mul_f32_e32 v26, v48, v26
	v_mul_f32_e32 v27, v48, v27
	v_mul_f32_e32 v24, v48, v24
	v_mul_f32_e32 v25, v48, v25
	v_mul_f32_e32 v22, v48, v22
	v_mul_f32_e32 v23, v48, v23
	v_mul_f32_e32 v20, v48, v20
	v_mul_f32_e32 v21, v48, v21
	v_mul_f32_e32 v18, v48, v18
	v_mul_f32_e32 v19, v48, v19
	v_mul_f32_e32 v16, v48, v16
	v_mul_f32_e32 v17, v48, v17
	v_mul_f32_e32 v14, v48, v14
	v_mul_f32_e32 v15, v48, v15
	v_mul_f32_e32 v12, v48, v12
	v_mul_f32_e32 v13, v48, v13
	v_mul_f32_e32 v10, v48, v10
	v_mul_f32_e32 v11, v48, v11
	v_mul_f32_e32 v8, v48, v8
	v_mul_f32_e32 v9, v48, v9
	v_mul_f32_e32 v6, v48, v6
	v_mul_f32_e32 v7, v48, v7
	v_mul_f32_e32 v4, v48, v4
	v_mul_f32_e32 v5, v48, v5
	v_mul_f32_e32 v2, v48, v2
	v_mul_f32_e32 v3, v48, v3
	s_branch .LBB0_327

; #define LAS __attribute__((address_space(3)))
; #define MFMA32(a, b, c) __builtin_amdgcn_mfma_f32_32x32x16_bf16((a), (b), (c), 0, 0, 0)
; template <int MODE, bool UNI>
; DI void attn_compute(const bf16x8 (&qf)[4], const bf16x8 (&kf)[4], const bf16x8 (&vf)[2][2], int kt, int d00, const float* lut, float ubias, AttnSt& st,
;                      unsigned W, int win, int dmask, bool lane_sel) {
;     ...
;     const int d0 = d00 - s0;
;     const LAS float* lb = (const LAS float*)lut + ((MODE == 4) ? 16 * (d0 - 23) : (d0 - 23));
;     float bia[16];
;     if (!UNI) {
; #pragma unroll
;         for (int i = 0; i < 16; ++i) { const int ci = 16 * (i >> 3) + (i & 7); bia[i] = (MODE == 4) ? lb[16 * (23 - ci)] : lb[23 - ci]; }
;     }
;     f32x16 sx;
; #pragma unroll
;     for (int i = 0; i < 16; ++i) sx[i] = 0.f;
; #pragma unroll
;     for (int ks = 0; ks < 4; ++ks) sx = MFMA32(kf[ks], qf[ks], sx);
;     asm volatile("s_waitcnt lgkmcnt(0)" ::: "memory");
;     float sv[16]; float mx = NEGF;
; #pragma unroll
;     for (int i = 0; i < 16; ++i) {
;         const int ci = 16 * (i >> 3) + (i & 7);
;         const int dist = d0 - ci;
;         bool v;
;         if (MODE == 0) v = ((W >> ci) & 1u) != 0u;
;         else if (MODE == 1) v = ((unsigned)dist <= (unsigned)win) && ((dist & dmask) == 0);
;         else if (MODE == 2) v = lane_sel;
;         else v = dist >= 0;
;         const float bias = UNI ? ubias : bia[i];
;         float s = fmaf(sx[i], SC2, bias);
;         if (MODE == 0) { const unsigned t = (unsigned)__builtin_amdgcn_sbfe((int)W, ci, 1);
;             s = __uint_as_float((__float_as_uint(s) & t) | (__float_as_uint(NEGF) & ~t)); }
;         else s = v ? s : NEGF;
;         sv[i] = s; mx = fmaxf(mx, s);
;     }
;     mx = fmaxf(mx, __shfl_xor(mx, 32));
;     const float mnew = fmaxf(st.m, mx);
;     const float msafe = (mnew > -1e29f) ? mnew : 0.f;
;     if (__ballot(mnew > st.m) != 0ull) {
;         const float alpha = __builtin_amdgcn_exp2f(st.m - msafe);
;         st.l *= alpha; st.m = mnew;
; #pragma unroll
;         for (int i = 0; i < 16; ++i) { st.o0[i] *= alpha; st.o1[i] *= alpha; }
;     }
.LBB0_349:
	s_waitcnt lgkmcnt(0)
	v_mfma_f32_32x32x16_bf16 v[50:65], v[50:53], v[70:73], 0
	v_add_u32_e32 v0, s65, v105
	v_mfma_f32_32x32x16_bf16 v[50:65], v[90:93], v[66:69], v[50:65]
	v_mfma_f32_32x32x16_bf16 v[50:65], v[94:97], v[78:81], v[50:65]
	ds_read2_b32 v[14:15], v0 offset0:22 offset1:23
	ds_read2_b32 v[90:91], v0 offset0:20 offset1:21
	ds_read2_b32 v[92:93], v0 offset0:18 offset1:19
	ds_read2_b32 v[94:95], v0 offset0:16 offset1:17
	ds_read2_b32 v[96:97], v0 offset0:6 offset1:7
	ds_read2_b32 v[108:109], v0 offset0:4 offset1:5
	ds_read2_b32 v[110:111], v0 offset0:2 offset1:3
	ds_read2_b32 v[112:113], v0 offset1:1
	v_mfma_f32_32x32x16_bf16 v[50:65], v[86:89], v[74:77], v[50:65]
	s_waitcnt lgkmcnt(0)
	s_nop 10
	v_fmamk_f32 v0, v50, 0x3e38aa3b, v15
	v_fmac_f32_e32 v14, 0x3e38aa3b, v51
	v_fmamk_f32 v15, v52, 0x3e38aa3b, v91
	v_fmac_f32_e32 v90, 0x3e38aa3b, v53
	v_cndmask_b32_e64 v89, v239, v0, s[0:1]
	v_cndmask_b32_e64 v88, v239, v14, s[0:1]
	v_fmamk_f32 v50, v54, 0x3e38aa3b, v93
	v_fmac_f32_e32 v92, 0x3e38aa3b, v55
	v_cndmask_b32_e64 v87, v239, v15, s[0:1]
	v_cndmask_b32_e64 v86, v239, v90, s[0:1]
	v_max3_f32 v0, v89, s30, v88
	v_fmamk_f32 v51, v56, 0x3e38aa3b, v95
	v_fmac_f32_e32 v94, 0x3e38aa3b, v57
	v_fmac_f32_e32 v96, 0x3e38aa3b, v59
	v_fmamk_f32 v53, v60, 0x3e38aa3b, v109
	v_cndmask_b32_e64 v60, v239, v50, s[0:1]
	v_cndmask_b32_e64 v59, v239, v92, s[0:1]
	v_max3_f32 v0, v0, v87, v86
	v_fmamk_f32 v52, v58, 0x3e38aa3b, v97
	v_cndmask_b32_e64 v58, v239, v51, s[0:1]
	v_cndmask_b32_e64 v57, v239, v94, s[0:1]
	v_max3_f32 v0, v0, v60, v59
	v_cndmask_b32_e64 v51, v239, v52, s[0:1]
	v_cndmask_b32_e64 v50, v239, v96, s[0:1]
	v_max3_f32 v0, v0, v58, v57
	v_fmac_f32_e32 v108, 0x3e38aa3b, v61
	v_max3_f32 v0, v0, v51, v50
	v_cndmask_b32_e64 v52, v239, v53, s[0:1]
	v_cndmask_b32_e64 v53, v239, v108, s[0:1]
	v_fmamk_f32 v14, v62, 0x3e38aa3b, v111
	v_fmac_f32_e32 v110, 0x3e38aa3b, v63
	v_max3_f32 v0, v0, v52, v53
	v_cndmask_b32_e64 v54, v239, v14, s[0:1]
	v_cndmask_b32_e64 v55, v239, v110, s[0:1]
	v_fmamk_f32 v14, v64, 0x3e38aa3b, v113
	v_fmac_f32_e32 v112, 0x3e38aa3b, v65
	v_max3_f32 v0, v0, v54, v55
	v_cndmask_b32_e64 v56, v239, v14, s[0:1]
	v_cndmask_b32_e64 v14, v239, v112, s[0:1]
	v_max3_f32 v0, v0, v56, v14
	v_mov_b32_e32 v15, v0
	s_nop 1
	v_permlane32_swap_b32_e32 v15, v0
	s_waitcnt lgkmcnt(0)
	v_max3_f32 v0, v106, v0, v15
	v_cmp_lt_f32_e32 vcc, s12, v0
	s_nop 1
	v_cndmask_b32_e32 v15, 0, v0, vcc
	v_cmp_gt_f32_e32 vcc, v0, v106
	s_cbranch_vccz .LBB0_351
	v_sub_f32_e32 v61, v106, v15
	v_exp_f32_e32 v62, v61
	s_nop 0
	v_mul_f32_e32 v48, v48, v62
	v_mul_f32_e32 v46, v62, v46
	v_mul_f32_e32 v47, v62, v47
	v_mul_f32_e32 v44, v62, v44
	v_mul_f32_e32 v45, v62, v45
	v_mul_f32_e32 v42, v62, v42
	v_mul_f32_e32 v43, v62, v43
	v_mul_f32_e32 v40, v62, v40
	v_mul_f32_e32 v41, v62, v41
	v_mul_f32_e32 v38, v62, v38
	v_mul_f32_e32 v39, v62, v39
	v_mul_f32_e32 v36, v62, v36
	v_mul_f32_e32 v37, v62, v37
	v_mul_f32_e32 v34, v62, v34
	v_mul_f32_e32 v35, v62, v35
	v_mul_f32_e32 v32, v62, v32
	v_mul_f32_e32 v33, v62, v33
	v_mul_f32_e32 v30, v62, v30
	v_mul_f32_e32 v31, v62, v31
	v_mul_f32_e32 v28, v62, v28
	v_mul_f32_e32 v29, v62, v29
	v_mul_f32_e32 v26, v62, v26
	v_mul_f32_e32 v27, v62, v27
	v_mul_f32_e32 v24, v62, v24
	v_mul_f32_e32 v25, v62, v25
	v_mul_f32_e32 v22, v62, v22
	v_mul_f32_e32 v23, v62, v23
	v_mul_f32_e32 v20, v62, v20
	v_mul_f32_e32 v21, v62, v21
	v_mul_f32_e32 v18, v62, v18
	v_mul_f32_e32 v19, v62, v19
	v_mul_f32_e32 v16, v62, v16
	v_mul_f32_e32 v17, v62, v17
	s_branch .LBB0_352

; #define LAS __attribute__((address_space(3)))
; #define MFMA32(a, b, c) __builtin_amdgcn_mfma_f32_32x32x16_bf16((a), (b), (c), 0, 0, 0)
; template <int MODE, bool UNI>
; DI void attn_compute(const bf16x8 (&qf)[4], const bf16x8 (&kf)[4], const bf16x8 (&vf)[2][2], int kt, int d00, const float* lut, float ubias, AttnSt& st,
;                      unsigned W, int win, int dmask, bool lane_sel) {
;     ...
;     const int d0 = d00 - s0;
;     const LAS float* lb = (const LAS float*)lut + ((MODE == 4) ? 16 * (d0 - 23) : (d0 - 23));
;     float bia[16];
;     if (!UNI) {
; #pragma unroll
;         for (int i = 0; i < 16; ++i) { const int ci = 16 * (i >> 3) + (i & 7); bia[i] = (MODE == 4) ? lb[16 * (23 - ci)] : lb[23 - ci]; }
;     }
;     f32x16 sx;
; #pragma unroll
;     for (int i = 0; i < 16; ++i) sx[i] = 0.f;
; #pragma unroll
;     for (int ks = 0; ks < 4; ++ks) sx = MFMA32(kf[ks], qf[ks], sx);
;     asm volatile("s_waitcnt lgkmcnt(0)" ::: "memory");
;     float sv[16]; float mx = NEGF;
; #pragma unroll
;     for (int i = 0; i < 16; ++i) {
;         const int ci = 16 * (i >> 3) + (i & 7);
;         const int dist = d0 - ci;
;         bool v;
;         if (MODE == 0) v = ((W >> ci) & 1u) != 0u;
;         else if (MODE == 1) v = ((unsigned)dist <= (unsigned)win) && ((dist & dmask) == 0);
;         else if (MODE == 2) v = lane_sel;
;         else v = dist >= 0;
;         const float bias = UNI ? ubias : bia[i];
;         float s = fmaf(sx[i], SC2, bias);
;         if (MODE == 0) { const unsigned t = (unsigned)__builtin_amdgcn_sbfe((int)W, ci, 1);
;             s = __uint_as_float((__float_as_uint(s) & t) | (__float_as_uint(NEGF) & ~t)); }
;         else s = v ? s : NEGF;
;         sv[i] = s; mx = fmaxf(mx, s);
;     }
;     mx = fmaxf(mx, __shfl_xor(mx, 32));
;     const float mnew = fmaxf(st.m, mx);
;     const float msafe = (mnew > -1e29f) ? mnew : 0.f;
;     if (__ballot(mnew > st.m) != 0ull) {
;         const float alpha = __builtin_amdgcn_exp2f(st.m - msafe);
;         st.l *= alpha; st.m = mnew;
; #pragma unroll
;         for (int i = 0; i < 16; ++i) { st.o0[i] *= alpha; st.o1[i] *= alpha; }
;     }
.LBB0_361:
	s_waitcnt lgkmcnt(0)
	v_mfma_f32_32x32x16_bf16 v[50:65], v[50:53], v[70:73], 0
	v_cmp_lt_i32_e32 vcc, -1, v14
	v_mfma_f32_32x32x16_bf16 v[50:65], v[90:93], v[66:69], v[50:65]
	v_mfma_f32_32x32x16_bf16 v[50:65], v[94:97], v[78:81], v[50:65]
	ds_read2_b32 v[90:91], v15 offset0:22 offset1:23
	ds_read2_b32 v[92:93], v15 offset0:20 offset1:21
	ds_read2_b32 v[94:95], v15 offset0:18 offset1:19
	ds_read2_b32 v[96:97], v15 offset0:16 offset1:17
	ds_read2_b32 v[104:105], v15 offset0:6 offset1:7
	ds_read2_b32 v[106:107], v15 offset0:4 offset1:5
	ds_read2_b32 v[108:109], v15 offset0:2 offset1:3
	ds_read2_b32 v[110:111], v15 offset1:1
	v_mfma_f32_32x32x16_bf16 v[50:65], v[86:89], v[74:77], v[50:65]
	s_waitcnt lgkmcnt(0)
	s_nop 10
	v_fmamk_f32 v49, v50, 0x3e38aa3b, v91
	v_fmac_f32_e32 v90, 0x3e38aa3b, v51
	v_fmamk_f32 v51, v54, 0x3e38aa3b, v95
	v_cndmask_b32_e32 v54, v239, v49, vcc
	v_cmp_lt_i32_e32 vcc, 0, v14
	v_fmamk_f32 v50, v52, 0x3e38aa3b, v93
	v_fmac_f32_e32 v94, 0x3e38aa3b, v55
	v_cndmask_b32_e32 v55, v239, v90, vcc
	v_cmp_lt_i32_e32 vcc, 1, v14
	v_fmac_f32_e32 v92, 0x3e38aa3b, v53
	v_fmamk_f32 v53, v56, 0x3e38aa3b, v97
	v_cndmask_b32_e32 v56, v239, v50, vcc
	v_cmp_lt_i32_e32 vcc, 2, v14
	v_fmac_f32_e32 v96, 0x3e38aa3b, v57
	v_fmac_f32_e32 v104, 0x3e38aa3b, v59
	v_cndmask_b32_e32 v50, v239, v92, vcc
	v_cmp_lt_i32_e32 vcc, 3, v14
	v_max3_f32 v49, v54, s30, v55
	v_max3_f32 v49, v49, v56, v50
	v_cndmask_b32_e32 v51, v239, v51, vcc
	v_cmp_lt_i32_e32 vcc, 4, v14
	v_fmac_f32_e32 v106, 0x3e38aa3b, v61
	v_fmac_f32_e32 v108, 0x3e38aa3b, v63
	v_cndmask_b32_e32 v52, v239, v94, vcc
	v_cmp_lt_i32_e32 vcc, 5, v14
	v_max3_f32 v49, v49, v51, v52
	v_fmac_f32_e32 v110, 0x3e38aa3b, v65
	v_cndmask_b32_e32 v86, v239, v53, vcc
	v_cmp_lt_i32_e32 vcc, 6, v14
	v_fmamk_f32 v53, v58, 0x3e38aa3b, v105
	s_nop 0
	v_cndmask_b32_e32 v87, v239, v96, vcc
	v_cmp_lt_i32_e32 vcc, 15, v14
	v_max3_f32 v49, v49, v86, v87
	s_nop 0
	v_cndmask_b32_e32 v58, v239, v53, vcc
	v_cmp_lt_i32_e32 vcc, 16, v14
	v_fmamk_f32 v53, v60, 0x3e38aa3b, v107
	s_nop 0
	v_cndmask_b32_e32 v59, v239, v104, vcc
	v_cmp_lt_i32_e32 vcc, 17, v14
	v_max3_f32 v49, v49, v58, v59
	s_nop 0
	v_cndmask_b32_e32 v60, v239, v53, vcc
	v_cmp_lt_i32_e32 vcc, 18, v14
	v_fmamk_f32 v53, v62, 0x3e38aa3b, v109
	s_nop 0
	v_cndmask_b32_e32 v61, v239, v106, vcc
	v_cmp_lt_i32_e32 vcc, 19, v14
	v_max3_f32 v49, v49, v60, v61
	s_nop 0
	v_cndmask_b32_e32 v62, v239, v53, vcc
	v_cmp_lt_i32_e32 vcc, 20, v14
	v_fmamk_f32 v53, v64, 0x3e38aa3b, v111
	s_nop 0
	v_cndmask_b32_e32 v63, v239, v108, vcc
	v_cmp_lt_i32_e32 vcc, 21, v14
	v_max3_f32 v49, v49, v62, v63
	s_nop 0
	v_cndmask_b32_e32 v64, v239, v53, vcc
	v_cmp_lt_i32_e32 vcc, 22, v14
	s_nop 1
	v_cndmask_b32_e32 v53, v239, v110, vcc
	v_max3_f32 v49, v49, v64, v53
	v_mov_b32_e32 v57, v49
	s_nop 1
	v_permlane32_swap_b32_e32 v57, v49
	s_waitcnt lgkmcnt(0)
	v_max3_f32 v49, v0, v49, v57
	v_cmp_lt_f32_e32 vcc, s12, v49
	s_nop 1
	v_cndmask_b32_e32 v57, 0, v49, vcc
	v_cmp_gt_f32_e32 vcc, v49, v0
	s_cbranch_vccz .LBB0_363
	v_sub_f32_e32 v0, v0, v57
	v_exp_f32_e32 v0, v0
	s_nop 0
	v_mul_f32_e32 v48, v48, v0
	v_mul_f32_e32 v46, v0, v46
	v_mul_f32_e32 v47, v0, v47
	v_mul_f32_e32 v44, v0, v44
	v_mul_f32_e32 v45, v0, v45
	v_mul_f32_e32 v42, v0, v42
	v_mul_f32_e32 v43, v0, v43
	v_mul_f32_e32 v40, v0, v40
	v_mul_f32_e32 v41, v0, v41
	v_mul_f32_e32 v38, v0, v38
	v_mul_f32_e32 v39, v0, v39
	v_mul_f32_e32 v36, v0, v36
	v_mul_f32_e32 v37, v0, v37
	v_mul_f32_e32 v34, v0, v34
	v_mul_f32_e32 v35, v0, v35
	v_mul_f32_e32 v32, v0, v32
	v_mul_f32_e32 v33, v0, v33
	v_mul_f32_e32 v30, v0, v30
	v_mul_f32_e32 v31, v0, v31
	v_mul_f32_e32 v28, v0, v28
	v_mul_f32_e32 v29, v0, v29
	v_mul_f32_e32 v26, v0, v26
	v_mul_f32_e32 v27, v0, v27
	v_mul_f32_e32 v24, v0, v24
	v_mul_f32_e32 v25, v0, v25
	v_mul_f32_e32 v22, v0, v22
	v_mul_f32_e32 v23, v0, v23
	v_mul_f32_e32 v20, v0, v20
	v_mul_f32_e32 v21, v0, v21
	v_mul_f32_e32 v18, v0, v18
	v_mul_f32_e32 v19, v0, v19
	v_mul_f32_e32 v16, v0, v16
	v_mul_f32_e32 v17, v0, v17
	s_branch .LBB0_364

; #define LAS __attribute__((address_space(3)))
; #define MFMA32(a, b, c) __builtin_amdgcn_mfma_f32_32x32x16_bf16((a), (b), (c), 0, 0, 0)
; template <int MODE, bool UNI>
; DI void attn_compute(const bf16x8 (&qf)[4], const bf16x8 (&kf)[4], const bf16x8 (&vf)[2][2], int kt, int d00, const float* lut, float ubias, AttnSt& st,
;                      unsigned W, int win, int dmask, bool lane_sel) {
;     ...
;     const int d0 = d00 - s0;
;     const LAS float* lb = (const LAS float*)lut + ((MODE == 4) ? 16 * (d0 - 23) : (d0 - 23));
;     float bia[16];
;     if (!UNI) {
; #pragma unroll
;         for (int i = 0; i < 16; ++i) { const int ci = 16 * (i >> 3) + (i & 7); bia[i] = (MODE == 4) ? lb[16 * (23 - ci)] : lb[23 - ci]; }
;     }
;     f32x16 sx;
; #pragma unroll
;     for (int i = 0; i < 16; ++i) sx[i] = 0.f;
; #pragma unroll
;     for (int ks = 0; ks < 4; ++ks) sx = MFMA32(kf[ks], qf[ks], sx);
;     asm volatile("s_waitcnt lgkmcnt(0)" ::: "memory");
;     float sv[16]; float mx = NEGF;
; #pragma unroll
;     for (int i = 0; i < 16; ++i) {
;         const int ci = 16 * (i >> 3) + (i & 7);
;         const int dist = d0 - ci;
;         bool v;
;         if (MODE == 0) v = ((W >> ci) & 1u) != 0u;
;         else if (MODE == 1) v = ((unsigned)dist <= (unsigned)win) && ((dist & dmask) == 0);
;         else if (MODE == 2) v = lane_sel;
;         else v = dist >= 0;
;         const float bias = UNI ? ubias : bia[i];
;         float s = fmaf(sx[i], SC2, bias);
;         if (MODE == 0) { const unsigned t = (unsigned)__builtin_amdgcn_sbfe((int)W, ci, 1);
;             s = __uint_as_float((__float_as_uint(s) & t) | (__float_as_uint(NEGF) & ~t)); }
;         else s = v ? s : NEGF;
;         sv[i] = s; mx = fmaxf(mx, s);
;     }
;     mx = fmaxf(mx, __shfl_xor(mx, 32));
;     const float mnew = fmaxf(st.m, mx);
;     const float msafe = (mnew > -1e29f) ? mnew : 0.f;
;     if (__ballot(mnew > st.m) != 0ull) {
;         const float alpha = __builtin_amdgcn_exp2f(st.m - msafe);
;         st.l *= alpha; st.m = mnew;
; #pragma unroll
;         for (int i = 0; i < 16; ++i) { st.o0[i] *= alpha; st.o1[i] *= alpha; }
;     }
.LBB0_524:
	s_waitcnt lgkmcnt(0)
	v_mfma_f32_32x32x16_bf16 v[34:49], v[34:37], v[50:53], 0
	v_add_u32_e32 v161, 0x400, v129
	v_cmp_lt_i32_e32 vcc, -1, v159
	v_mfma_f32_32x32x16_bf16 v[34:49], v[90:93], v[54:57], v[34:49]
	ds_read2_b32 v[90:91], v161 offset0:96 offset1:112
	v_mfma_f32_32x32x16_bf16 v[34:49], v[86:89], v[58:61], v[34:49]
	ds_read2_b32 v[86:87], v161 offset0:64 offset1:80
	ds_read2_b32 v[88:89], v161 offset0:32 offset1:48
	ds_read2_b32 v[92:93], v129 offset0:96 offset1:112
	ds_read2_b32 v[162:163], v129 offset0:64 offset1:80
	ds_read2_b32 v[164:165], v129 offset0:32 offset1:48
	ds_read2_b32 v[166:167], v129 offset1:16
	ds_read2_b32 v[168:169], v161 offset1:16
	s_waitcnt lgkmcnt(0)
	v_mfma_f32_32x32x16_bf16 v[34:49], v[82:85], v[62:65], v[34:49]
	s_waitcnt lgkmcnt(0)
	s_nop 10
	v_fmamk_f32 v34, v34, 0x3e38aa3b, v91
	v_fmac_f32_e32 v90, 0x3e38aa3b, v35
	v_cndmask_b32_e32 v35, v239, v34, vcc
	v_cmp_lt_i32_e32 vcc, 0, v159
	v_fmamk_f32 v36, v36, 0x3e38aa3b, v87
	v_fmac_f32_e32 v88, 0x3e38aa3b, v39
	v_cndmask_b32_e32 v39, v239, v90, vcc
	v_cmp_lt_i32_e32 vcc, 1, v159
	v_fmac_f32_e32 v86, 0x3e38aa3b, v37
	v_fmamk_f32 v82, v40, 0x3e38aa3b, v169
	v_cndmask_b32_e32 v40, v239, v36, vcc
	v_cmp_lt_i32_e32 vcc, 2, v159
	v_fmamk_f32 v37, v38, 0x3e38aa3b, v89
	v_fmac_f32_e32 v168, 0x3e38aa3b, v41
	v_cndmask_b32_e32 v36, v239, v86, vcc
	v_cmp_lt_i32_e32 vcc, 3, v159
	v_fmamk_f32 v41, v42, 0x3e38aa3b, v93
	v_fmac_f32_e32 v92, 0x3e38aa3b, v43
	v_cndmask_b32_e32 v37, v239, v37, vcc
	v_cmp_lt_i32_e32 vcc, 4, v159
	v_max3_f32 v34, v35, s30, v39
	v_max3_f32 v34, v34, v40, v36
	v_cndmask_b32_e32 v38, v239, v88, vcc
	v_cmp_lt_i32_e32 vcc, 5, v159
	v_fmac_f32_e32 v162, 0x3e38aa3b, v45
	v_max3_f32 v34, v34, v37, v38
	v_cndmask_b32_e32 v82, v239, v82, vcc
	v_cmp_lt_i32_e32 vcc, 6, v159
	v_fmac_f32_e32 v164, 0x3e38aa3b, v47
	v_fmac_f32_e32 v166, 0x3e38aa3b, v49
	v_cndmask_b32_e32 v83, v239, v168, vcc
	v_cmp_lt_i32_e32 vcc, 15, v159
	v_max3_f32 v34, v34, v82, v83
	s_nop 0
	v_cndmask_b32_e32 v84, v239, v41, vcc
	v_cmp_lt_i32_e32 vcc, 16, v159
	v_fmamk_f32 v41, v44, 0x3e38aa3b, v163
	s_nop 0
	v_cndmask_b32_e32 v43, v239, v92, vcc
	v_cmp_lt_i32_e32 vcc, 17, v159
	v_max3_f32 v34, v34, v84, v43
	s_nop 0
	v_cndmask_b32_e32 v44, v239, v41, vcc
	v_cmp_lt_i32_e32 vcc, 18, v159
	v_fmamk_f32 v41, v46, 0x3e38aa3b, v165
	s_nop 0
	v_cndmask_b32_e32 v45, v239, v162, vcc
	v_cmp_lt_i32_e32 vcc, 19, v159
	v_max3_f32 v34, v34, v44, v45
	s_nop 0
	v_cndmask_b32_e32 v46, v239, v41, vcc
	v_cmp_lt_i32_e32 vcc, 20, v159
	v_fmamk_f32 v41, v48, 0x3e38aa3b, v167
	s_nop 0
	v_cndmask_b32_e32 v47, v239, v164, vcc
	v_cmp_lt_i32_e32 vcc, 21, v159
	v_max3_f32 v34, v34, v46, v47
	s_nop 0
	v_cndmask_b32_e32 v48, v239, v41, vcc
	v_cmp_lt_i32_e32 vcc, 22, v159
	s_nop 1
	v_cndmask_b32_e32 v41, v239, v166, vcc
	v_max3_f32 v34, v34, v48, v41
	ds_bpermute_b32 v42, v148, v34
	s_waitcnt lgkmcnt(0)
	v_max3_f32 v34, v160, v34, v42
	v_cmp_lt_f32_e32 vcc, s12, v34
	s_nop 1
	v_cndmask_b32_e32 v42, 0, v34, vcc
	v_cmp_gt_f32_e32 vcc, v34, v160
	s_cbranch_vccz .LBB0_526
	v_sub_f32_e32 v49, v160, v42
	v_exp_f32_e32 v86, v49
	s_nop 0
	v_mul_f32_e32 v99, v99, v86
	v_mul_f32_e32 v16, v86, v16
	v_mul_f32_e32 v17, v86, v17
	v_mul_f32_e32 v14, v86, v14
	v_mul_f32_e32 v15, v86, v15
	v_mul_f32_e32 v12, v86, v12
	v_mul_f32_e32 v13, v86, v13
	v_mul_f32_e32 v10, v86, v10
	v_mul_f32_e32 v11, v86, v11
	v_mul_f32_e32 v8, v86, v8
	v_mul_f32_e32 v9, v86, v9
	v_mul_f32_e32 v6, v86, v6
	v_mul_f32_e32 v7, v86, v7
	v_mul_f32_e32 v4, v86, v4
	v_mul_f32_e32 v5, v86, v5
	v_mul_f32_e32 v2, v86, v2
	v_mul_f32_e32 v3, v86, v3
	v_mul_f32_e32 v32, v86, v32
	v_mul_f32_e32 v33, v86, v33
	v_mul_f32_e32 v30, v86, v30
	v_mul_f32_e32 v31, v86, v31
	v_mul_f32_e32 v28, v86, v28
	v_mul_f32_e32 v29, v86, v29
	v_mul_f32_e32 v26, v86, v26
	v_mul_f32_e32 v27, v86, v27
	v_mul_f32_e32 v24, v86, v24
	v_mul_f32_e32 v25, v86, v25
	v_mul_f32_e32 v22, v86, v22
	v_mul_f32_e32 v23, v86, v23
	v_mul_f32_e32 v20, v86, v20
	v_mul_f32_e32 v21, v86, v21
	v_mul_f32_e32 v18, v86, v18
	v_mul_f32_e32 v19, v86, v19
	s_branch .LBB0_527
